# same as v58 (XCD-local barriers on 18 seams with runtime XCC-placement check + setprio cleanup), barrier-leader temporaries moved to registers the census already clobbers
# speedup vs baseline: 1.0201x; 1.0061x over previous
.LBB0_95:
	s_andn2_saveexec_b64 s[6:7], s[6:7]
	s_cbranch_execz .LBB0_115
	s_mov_b64 s[6:7], exec
	s_mov_b32 s1, 0xcd99adac
	s_lshr_b32 s1, s1, s21
	s_bitcmp1_b32 s1, 0
	s_cbranch_scc0 .Lbar_full
	v_mov_b32_e32 v12, 0x23808
	ds_read_b32 v13, v12
	s_waitcnt lgkmcnt(0)
	v_readfirstlane_b32 s1, v13
	s_cmp_lg_u32 s1, 0
	s_cbranch_scc1 .Lbar_have_flag
	v_mov_b32_e32 v14, 0x3600
	global_load_dwordx4 v[4:7], v14, s[24:25] sc1
	global_load_dwordx4 v[8:11], v14, s[24:25] offset:16 sc1
	s_waitcnt vmcnt(0)
	v_add_u32_e32 v13, -1, v4
	v_and_b32_e32 v15, v13, v4
	v_min_u32_e32 v14, v4, v5
	v_add_u32_e32 v13, -1, v5
	v_and_b32_e32 v13, v13, v5
	v_or_b32_e32 v15, v15, v13
	v_add_u32_e32 v13, -1, v6
	v_and_b32_e32 v13, v13, v6
	v_or_b32_e32 v15, v15, v13
	v_min_u32_e32 v14, v14, v6
	v_add_u32_e32 v13, -1, v7
	v_and_b32_e32 v13, v13, v7
	v_or_b32_e32 v15, v15, v13
	v_min_u32_e32 v14, v14, v7
	v_add_u32_e32 v13, -1, v8
	v_and_b32_e32 v13, v13, v8
	v_or_b32_e32 v15, v15, v13
	v_min_u32_e32 v14, v14, v8
	v_add_u32_e32 v13, -1, v9
	v_and_b32_e32 v13, v13, v9
	v_or_b32_e32 v15, v15, v13
	v_min_u32_e32 v14, v14, v9
	v_add_u32_e32 v13, -1, v10
	v_and_b32_e32 v13, v13, v10
	v_or_b32_e32 v15, v15, v13
	v_min_u32_e32 v14, v14, v10
	v_add_u32_e32 v13, -1, v11
	v_and_b32_e32 v13, v13, v11
	v_or_b32_e32 v15, v15, v13
	v_min_u32_e32 v14, v14, v11
	v_cmp_eq_u32_e32 vcc, 0, v15
	v_cmp_ne_u32_e64 s[10:11], 0, v14
	s_and_b64 s[10:11], s[10:11], vcc
	v_cndmask_b32_e64 v13, 2, 1, s[10:11]
	ds_write_b32 v12, v13
	s_nop 1
	v_readfirstlane_b32 s1, v13
